# GEMM k-loops: DMA pieces evenly spread over the 16 MFMAs (after MFMA 0,3,5,8,11,13), saddr DMA, lgkmcnt(6), tail loop
# speedup vs baseline: 1.0309x; 1.0005x over previous
.Lgemm_g1_main:
	s_add_i32 s18, s11, 0
	v_add_u32_e32 v182, s18, v178
	v_add_u32_e32 v152, v182, v180
	ds_read_b128 v[172:175], v152
	ds_read_b128 v[168:171], v152 offset:2048
	ds_read_b128 v[156:159], v152 offset:4096
	ds_read_b128 v[152:155], v152 offset:6144
	v_add_u32_e32 v183, s18, v179
	v_add_u32_e32 v160, v183, v180
	ds_read_b128 v[164:167], v160 offset:16384
	ds_read_b128 v[160:163], v160 offset:18432
	s_add_i32 s18, s0, s10
	s_mov_b32 m0, s18
	v_mfma_f32_32x32x16_bf16 v[112:127], v[136:139], v[148:151], v[112:127]
	global_load_lds_dwordx4 v176, s[74:75]
	v_mfma_f32_32x32x16_bf16 v[96:111], v[132:135], v[148:151], v[96:111]
	v_mfma_f32_32x32x16_bf16 v[80:95], v[136:139], v[144:147], v[80:95]
	s_add_i32 m0, s18, 0x1000
	s_add_u32 s98, s74, 0x1000
	s_addc_u32 s99, s75, 0
	v_mfma_f32_32x32x16_bf16 v[64:79], v[132:135], v[144:147], v[64:79]
	global_load_lds_dwordx4 v176, s[98:99]
	v_mfma_f32_32x32x16_bf16 v[48:63], v[136:139], v[140:143], v[48:63]
	s_add_i32 m0, s18, 0x2000
	s_add_u32 s100, s74, 0x2000
	s_addc_u32 s101, s75, 0
	v_mfma_f32_32x32x16_bf16 v[32:47], v[132:135], v[140:143], v[32:47]
	global_load_lds_dwordx4 v176, s[100:101]
	v_mfma_f32_32x32x16_bf16 v[16:31], v[136:139], v[128:131], v[16:31]
	v_mfma_f32_32x32x16_bf16 v[0:15], v[132:135], v[128:131], v[0:15]
	v_add_u32_e32 v128, v182, v181
	ds_read_b128 v[148:151], v128
	ds_read_b128 v[144:147], v128 offset:2048
	ds_read_b128 v[140:143], v128 offset:4096
	ds_read_b128 v[128:131], v128 offset:6144
	v_add_u32_e32 v132, v183, v181
	ds_read_b128 v[136:139], v132 offset:16384
	ds_read_b128 v[132:135], v132 offset:18432
	s_waitcnt lgkmcnt(6)
	s_add_i32 m0, s18, 0x3000
	s_add_u32 s98, s74, 0x3000
	s_addc_u32 s99, s75, 0
	v_mfma_f32_32x32x16_bf16 v[112:127], v[164:167], v[172:175], v[112:127]
	global_load_lds_dwordx4 v176, s[98:99]
	v_mfma_f32_32x32x16_bf16 v[96:111], v[160:163], v[172:175], v[96:111]
	v_mfma_f32_32x32x16_bf16 v[80:95], v[164:167], v[168:171], v[80:95]
	s_add_i32 m0, s18, 0x4000
	v_mfma_f32_32x32x16_bf16 v[64:79], v[160:163], v[168:171], v[64:79]
	global_load_lds_dwordx4 v176, s[72:73]
	v_mfma_f32_32x32x16_bf16 v[48:63], v[164:167], v[156:159], v[48:63]
	s_add_i32 m0, s18, 0x5000
	s_add_u32 s98, s72, 0x1000
	s_addc_u32 s99, s73, 0
	v_mfma_f32_32x32x16_bf16 v[32:47], v[160:163], v[156:159], v[32:47]
	global_load_lds_dwordx4 v176, s[98:99]
	v_mfma_f32_32x32x16_bf16 v[16:31], v[164:167], v[152:155], v[16:31]
	v_mfma_f32_32x32x16_bf16 v[0:15], v[160:163], v[152:155], v[0:15]
	s_add_u32 s74, s74, 0x80000
	s_addc_u32 s75, s75, 0
	s_add_u32 s72, s72, 0x5e000
	s_addc_u32 s73, s73, 0
	s_add_i32 s18, s10, 0x6000
	s_cmpk_lg_u32 s10, 0xc000
	s_cselect_b32 s10, s18, 0
	s_add_i32 s18, s11, 0x6000
	s_cmpk_lg_u32 s11, 0xc000
	s_cselect_b32 s11, s18, 0
	s_add_i32 s1, s1, 1
	s_waitcnt vmcnt(6) lgkmcnt(0)
	s_barrier
	s_cmp_lg_u32 s1, 62
	s_cbranch_scc1 .Lgemm_g1_main

.Lgemm_g2_main:
	s_add_i32 s18, s11, 0
	v_add_u32_e32 v182, s18, v178
	v_add_u32_e32 v152, v182, v180
	ds_read_b128 v[172:175], v152
	ds_read_b128 v[168:171], v152 offset:2048
	ds_read_b128 v[156:159], v152 offset:4096
	ds_read_b128 v[152:155], v152 offset:6144
	v_add_u32_e32 v183, s18, v179
	v_add_u32_e32 v160, v183, v180
	ds_read_b128 v[164:167], v160 offset:16384
	ds_read_b128 v[160:163], v160 offset:18432
	s_add_i32 s18, s0, s10
	s_mov_b32 m0, s18
	v_mfma_f32_32x32x16_bf16 v[112:127], v[148:151], v[132:135], v[112:127]
	global_load_lds_dwordx4 v176, s[68:69]
	v_mfma_f32_32x32x16_bf16 v[96:111], v[148:151], v[136:139], v[96:111]
	v_mfma_f32_32x32x16_bf16 v[80:95], v[144:147], v[132:135], v[80:95]
	s_add_i32 m0, s18, 0x1000
	s_add_u32 s98, s68, 0x1000
	s_addc_u32 s99, s69, 0
	v_mfma_f32_32x32x16_bf16 v[64:79], v[144:147], v[136:139], v[64:79]
	global_load_lds_dwordx4 v176, s[98:99]
	v_mfma_f32_32x32x16_bf16 v[48:63], v[140:143], v[132:135], v[48:63]
	s_add_i32 m0, s18, 0x2000
	s_add_u32 s100, s68, 0x2000
	s_addc_u32 s101, s69, 0
	v_mfma_f32_32x32x16_bf16 v[32:47], v[140:143], v[136:139], v[32:47]
	global_load_lds_dwordx4 v176, s[100:101]
	v_mfma_f32_32x32x16_bf16 v[16:31], v[128:131], v[132:135], v[16:31]
	v_mfma_f32_32x32x16_bf16 v[0:15], v[128:131], v[136:139], v[0:15]
	v_add_u32_e32 v128, v182, v181
	ds_read_b128 v[148:151], v128
	ds_read_b128 v[144:147], v128 offset:2048
	ds_read_b128 v[140:143], v128 offset:4096
	ds_read_b128 v[128:131], v128 offset:6144
	v_add_u32_e32 v136, v183, v181
	ds_read_b128 v[132:135], v136 offset:16384
	ds_read_b128 v[136:139], v136 offset:18432
	s_waitcnt lgkmcnt(6)
	s_add_i32 m0, s18, 0x3000
	s_add_u32 s98, s68, 0x3000
	s_addc_u32 s99, s69, 0
	v_mfma_f32_32x32x16_bf16 v[112:127], v[172:175], v[164:167], v[112:127]
	global_load_lds_dwordx4 v176, s[98:99]
	v_mfma_f32_32x32x16_bf16 v[96:111], v[172:175], v[160:163], v[96:111]
	v_mfma_f32_32x32x16_bf16 v[80:95], v[168:171], v[164:167], v[80:95]
	s_add_i32 m0, s18, 0x4000
	v_mfma_f32_32x32x16_bf16 v[64:79], v[168:171], v[160:163], v[64:79]
	global_load_lds_dwordx4 v176, s[70:71]
	v_mfma_f32_32x32x16_bf16 v[48:63], v[156:159], v[164:167], v[48:63]
	s_add_i32 m0, s18, 0x5000
	s_add_u32 s98, s70, 0x1000
	s_addc_u32 s99, s71, 0
	v_mfma_f32_32x32x16_bf16 v[32:47], v[156:159], v[160:163], v[32:47]
	global_load_lds_dwordx4 v176, s[98:99]
	v_mfma_f32_32x32x16_bf16 v[16:31], v[152:155], v[164:167], v[16:31]
	v_mfma_f32_32x32x16_bf16 v[0:15], v[152:155], v[160:163], v[0:15]
	s_add_u32 s68, s68, 0x80000
	s_addc_u32 s69, s69, 0
	s_add_u32 s70, s70, 0x5e000
	s_addc_u32 s71, s71, 0
	s_add_i32 s18, s10, 0x6000
	s_cmpk_lg_u32 s10, 0xc000
	s_cselect_b32 s10, s18, 0
	s_add_i32 s18, s11, 0x6000
	s_cmpk_lg_u32 s11, 0xc000
	s_cselect_b32 s11, s18, 0
	s_add_i32 s1, s1, 1
	s_waitcnt vmcnt(6) lgkmcnt(0)
	s_barrier
	s_cmp_lg_u32 s1, 62
	s_cbranch_scc1 .Lgemm_g2_main

.Lgemm_g3_main:
	s_add_i32 s79, s37, 0
	v_add_u32_e32 v182, s79, v178
	v_add_u32_e32 v152, v182, v180
	ds_read_b128 v[172:175], v152
	ds_read_b128 v[168:171], v152 offset:2048
	ds_read_b128 v[156:159], v152 offset:4096
	ds_read_b128 v[152:155], v152 offset:6144
	v_add_u32_e32 v183, s79, v179
	v_add_u32_e32 v160, v183, v180
	ds_read_b128 v[164:167], v160 offset:16384
	ds_read_b128 v[160:163], v160 offset:18432
	s_add_i32 s8, s22, s36
	s_mov_b32 m0, s8
	v_mfma_f32_32x32x16_bf16 v[112:127], v[148:151], v[132:135], v[112:127]
	global_load_lds_dwordx4 v176, s[6:7]
	v_mfma_f32_32x32x16_bf16 v[96:111], v[148:151], v[136:139], v[96:111]
	v_mfma_f32_32x32x16_bf16 v[80:95], v[144:147], v[132:135], v[80:95]
	s_add_i32 m0, s8, 0x1000
	s_add_u32 s98, s6, 0x1000
	s_addc_u32 s99, s7, 0
	v_mfma_f32_32x32x16_bf16 v[64:79], v[144:147], v[136:139], v[64:79]
	global_load_lds_dwordx4 v176, s[98:99]
	v_mfma_f32_32x32x16_bf16 v[48:63], v[140:143], v[132:135], v[48:63]
	s_add_i32 m0, s8, 0x2000
	s_add_u32 s100, s6, 0x2000
	s_addc_u32 s101, s7, 0
	v_mfma_f32_32x32x16_bf16 v[32:47], v[140:143], v[136:139], v[32:47]
	global_load_lds_dwordx4 v176, s[100:101]
	v_mfma_f32_32x32x16_bf16 v[16:31], v[128:131], v[132:135], v[16:31]
	v_mfma_f32_32x32x16_bf16 v[0:15], v[128:131], v[136:139], v[0:15]
	v_add_u32_e32 v128, v182, v181
	ds_read_b128 v[148:151], v128
	ds_read_b128 v[144:147], v128 offset:2048
	ds_read_b128 v[140:143], v128 offset:4096
	ds_read_b128 v[128:131], v128 offset:6144
	v_add_u32_e32 v136, v183, v181
	ds_read_b128 v[132:135], v136 offset:16384
	ds_read_b128 v[136:139], v136 offset:18432
	s_waitcnt lgkmcnt(6)
	s_add_i32 m0, s8, 0x3000
	s_add_u32 s98, s6, 0x3000
	s_addc_u32 s99, s7, 0
	v_mfma_f32_32x32x16_bf16 v[112:127], v[172:175], v[164:167], v[112:127]
	global_load_lds_dwordx4 v176, s[98:99]
	v_mfma_f32_32x32x16_bf16 v[96:111], v[172:175], v[160:163], v[96:111]
	v_mfma_f32_32x32x16_bf16 v[80:95], v[168:171], v[164:167], v[80:95]
	s_add_i32 m0, s8, 0x4000
	v_mfma_f32_32x32x16_bf16 v[64:79], v[168:171], v[160:163], v[64:79]
	global_load_lds_dwordx4 v176, s[4:5]
	v_mfma_f32_32x32x16_bf16 v[48:63], v[156:159], v[164:167], v[48:63]
	s_add_i32 m0, s8, 0x5000
	s_add_u32 s98, s4, 0x1000
	s_addc_u32 s99, s5, 0
	v_mfma_f32_32x32x16_bf16 v[32:47], v[156:159], v[160:163], v[32:47]
	global_load_lds_dwordx4 v176, s[98:99]
	v_mfma_f32_32x32x16_bf16 v[16:31], v[152:155], v[164:167], v[16:31]
	v_mfma_f32_32x32x16_bf16 v[0:15], v[152:155], v[160:163], v[0:15]
	s_add_u32 s6, s6, 0x80000
	s_addc_u32 s7, s7, 0
	s_add_u32 s4, s4, 0x20000
	s_addc_u32 s5, s5, 0
	s_add_i32 s8, s36, 0x6000
	s_cmpk_lg_u32 s36, 0xc000
	s_cselect_b32 s36, s8, 0
	s_add_i32 s8, s37, 0x6000
	s_cmpk_lg_u32 s37, 0xc000
	s_cselect_b32 s37, s8, 0
	s_add_i32 s33, s33, 1
	s_waitcnt vmcnt(6) lgkmcnt(0)
	s_barrier
	s_cmp_lg_u32 s33, 6
	s_cbranch_scc1 .Lgemm_g3_main

.Lgemm_g4_main:
	s_add_i32 s33, s22, 0
	v_add_u32_e32 v182, s33, v178
	v_add_u32_e32 v152, v182, v180
	ds_read_b128 v[172:175], v152
	ds_read_b128 v[168:171], v152 offset:2048
	ds_read_b128 v[156:159], v152 offset:4096
	ds_read_b128 v[152:155], v152 offset:6144
	v_add_u32_e32 v183, s33, v179
	v_add_u32_e32 v160, v183, v180
	ds_read_b128 v[164:167], v160 offset:16384
	ds_read_b128 v[160:163], v160 offset:18432
	s_add_i32 s8, s0, s11
	s_mov_b32 m0, s8
	v_mfma_f32_32x32x16_bf16 v[112:127], v[144:147], v[148:151], v[112:127]
	global_load_lds_dwordx4 v176, s[6:7]
	v_mfma_f32_32x32x16_bf16 v[96:111], v[132:135], v[148:151], v[96:111]
	v_mfma_f32_32x32x16_bf16 v[80:95], v[144:147], v[140:143], v[80:95]
	s_add_i32 m0, s8, 0x1000
	s_add_u32 s98, s6, 0x1000
	s_addc_u32 s99, s7, 0
	v_mfma_f32_32x32x16_bf16 v[64:79], v[132:135], v[140:143], v[64:79]
	global_load_lds_dwordx4 v176, s[98:99]
	v_mfma_f32_32x32x16_bf16 v[48:63], v[144:147], v[136:139], v[48:63]
	s_add_i32 m0, s8, 0x2000
	s_add_u32 s100, s6, 0x2000
	s_addc_u32 s101, s7, 0
	v_mfma_f32_32x32x16_bf16 v[32:47], v[132:135], v[136:139], v[32:47]
	global_load_lds_dwordx4 v176, s[100:101]
	v_mfma_f32_32x32x16_bf16 v[16:31], v[144:147], v[128:131], v[16:31]
	v_mfma_f32_32x32x16_bf16 v[0:15], v[132:135], v[128:131], v[0:15]
	v_add_u32_e32 v128, v182, v181
	ds_read_b128 v[148:151], v128
	ds_read_b128 v[140:143], v128 offset:2048
	ds_read_b128 v[136:139], v128 offset:4096
	ds_read_b128 v[128:131], v128 offset:6144
	v_add_u32_e32 v132, v183, v181
	ds_read_b128 v[144:147], v132 offset:16384
	ds_read_b128 v[132:135], v132 offset:18432
	s_waitcnt lgkmcnt(6)
	s_add_i32 m0, s8, 0x3000
	s_add_u32 s98, s6, 0x3000
	s_addc_u32 s99, s7, 0
	v_mfma_f32_32x32x16_bf16 v[112:127], v[164:167], v[172:175], v[112:127]
	global_load_lds_dwordx4 v176, s[98:99]
	v_mfma_f32_32x32x16_bf16 v[96:111], v[160:163], v[172:175], v[96:111]
	v_mfma_f32_32x32x16_bf16 v[80:95], v[164:167], v[168:171], v[80:95]
	s_add_i32 m0, s8, 0x4000
	v_mfma_f32_32x32x16_bf16 v[64:79], v[160:163], v[168:171], v[64:79]
	global_load_lds_dwordx4 v176, s[4:5]
	v_mfma_f32_32x32x16_bf16 v[48:63], v[164:167], v[156:159], v[48:63]
	s_add_i32 m0, s8, 0x5000
	s_add_u32 s98, s4, 0x1000
	s_addc_u32 s99, s5, 0
	v_mfma_f32_32x32x16_bf16 v[32:47], v[160:163], v[156:159], v[32:47]
	global_load_lds_dwordx4 v176, s[98:99]
	v_mfma_f32_32x32x16_bf16 v[16:31], v[164:167], v[152:155], v[16:31]
	v_mfma_f32_32x32x16_bf16 v[0:15], v[160:163], v[152:155], v[0:15]
	s_add_u32 s6, s6, 0x80000
	s_addc_u32 s7, s7, 0
	s_add_u32 s4, s4, 0x20000
	s_addc_u32 s5, s5, 0
	s_add_i32 s8, s11, 0x6000
	s_cmpk_lg_u32 s11, 0xc000
	s_cselect_b32 s11, s8, 0
	s_add_i32 s8, s22, 0x6000
	s_cmpk_lg_u32 s22, 0xc000
	s_cselect_b32 s22, s8, 0
	s_add_i32 s1, s1, 1
	s_waitcnt vmcnt(6) lgkmcnt(0)
	s_barrier
	s_cmp_lg_u32 s1, 6
	s_cbranch_scc1 .Lgemm_g4_main

.Lgemm_g5_main:
	s_add_i32 s22, s11, 0
	v_add_u32_e32 v183, s22, v179
	v_add_u32_e32 v152, v183, v181
	ds_read_b128 v[172:175], v152
	ds_read_b128 v[168:171], v152 offset:2048
	ds_read_b128 v[156:159], v152 offset:4096
	ds_read_b128 v[152:155], v152 offset:6144
	v_add_u32_e32 v184, s22, v180
	v_add_u32_e32 v160, v184, v181
	ds_read_b128 v[164:167], v160 offset:16384
	ds_read_b128 v[160:163], v160 offset:18432
	s_add_i32 s6, s1, s10
	s_mov_b32 m0, s6
	v_mfma_f32_32x32x16_bf16 v[112:127], v[148:151], v[144:147], v[112:127]
	global_load_lds_dwordx4 v176, s[76:77]
	v_mfma_f32_32x32x16_bf16 v[96:111], v[132:135], v[144:147], v[96:111]
	v_mfma_f32_32x32x16_bf16 v[80:95], v[148:151], v[140:143], v[80:95]
	s_add_i32 m0, s6, 0x1000
	s_add_u32 s98, s76, 0x1000
	s_addc_u32 s99, s77, 0
	v_mfma_f32_32x32x16_bf16 v[64:79], v[132:135], v[140:143], v[64:79]
	global_load_lds_dwordx4 v176, s[98:99]
	v_mfma_f32_32x32x16_bf16 v[48:63], v[148:151], v[136:139], v[48:63]
	s_add_i32 m0, s6, 0x2000
	s_add_u32 s100, s76, 0x2000
	s_addc_u32 s101, s77, 0
	v_mfma_f32_32x32x16_bf16 v[32:47], v[132:135], v[136:139], v[32:47]
	global_load_lds_dwordx4 v176, s[100:101]
	v_mfma_f32_32x32x16_bf16 v[16:31], v[148:151], v[128:131], v[16:31]
	v_mfma_f32_32x32x16_bf16 v[0:15], v[132:135], v[128:131], v[0:15]
	v_add_u32_e32 v128, v183, v182
	ds_read_b128 v[144:147], v128
	ds_read_b128 v[140:143], v128 offset:2048
	ds_read_b128 v[136:139], v128 offset:4096
	ds_read_b128 v[128:131], v128 offset:6144
	v_add_u32_e32 v132, v184, v182
	ds_read_b128 v[148:151], v132 offset:16384
	ds_read_b128 v[132:135], v132 offset:18432
	s_waitcnt lgkmcnt(6)
	s_add_i32 m0, s6, 0x3000
	s_add_u32 s98, s76, 0x3000
	s_addc_u32 s99, s77, 0
	v_mfma_f32_32x32x16_bf16 v[112:127], v[164:167], v[172:175], v[112:127]
	global_load_lds_dwordx4 v176, s[98:99]
	v_mfma_f32_32x32x16_bf16 v[96:111], v[160:163], v[172:175], v[96:111]
	v_mfma_f32_32x32x16_bf16 v[80:95], v[164:167], v[168:171], v[80:95]
	s_add_i32 m0, s6, 0x4000
	v_mfma_f32_32x32x16_bf16 v[64:79], v[160:163], v[168:171], v[64:79]
	global_load_lds_dwordx4 v176, s[4:5]
	v_mfma_f32_32x32x16_bf16 v[48:63], v[164:167], v[156:159], v[48:63]
	s_add_i32 m0, s6, 0x5000
	s_add_u32 s98, s4, 0x1000
	s_addc_u32 s99, s5, 0
	v_mfma_f32_32x32x16_bf16 v[32:47], v[160:163], v[156:159], v[32:47]
	global_load_lds_dwordx4 v176, s[98:99]
	v_mfma_f32_32x32x16_bf16 v[16:31], v[164:167], v[152:155], v[16:31]
	v_mfma_f32_32x32x16_bf16 v[0:15], v[160:163], v[152:155], v[0:15]
	s_add_u32 s76, s76, 0x80000
	s_addc_u32 s77, s77, 0
	s_add_u32 s4, s4, 0x18000
	s_addc_u32 s5, s5, 0
	s_add_i32 s6, s10, 0x6000
	s_cmpk_lg_u32 s10, 0xc000
	s_cselect_b32 s10, s6, 0
	s_add_i32 s6, s11, 0x6000
	s_cmpk_lg_u32 s11, 0xc000
	s_cselect_b32 s11, s6, 0
	s_add_i32 s9, s9, 1
	s_waitcnt vmcnt(6) lgkmcnt(0)
	s_barrier
	s_cmp_lg_u32 s9, 14
	s_cbranch_scc1 .Lgemm_g5_main

.Lgemm_g6_main:
	s_add_i32 s58, s76, 0
	v_add_u32_e32 v183, s58, v179
	v_add_u32_e32 v152, v183, v181
	ds_read_b128 v[172:175], v152
	ds_read_b128 v[168:171], v152 offset:2048
	ds_read_b128 v[156:159], v152 offset:4096
	ds_read_b128 v[152:155], v152 offset:6144
	v_add_u32_e32 v184, s58, v180
	v_add_u32_e32 v160, v184, v181
	ds_read_b128 v[164:167], v160 offset:16384
	ds_read_b128 v[160:163], v160 offset:18432
	s_add_i32 s56, s49, s75
	s_mov_b32 m0, s56
	v_mfma_f32_32x32x16_bf16 v[112:127], v[136:139], v[148:151], v[112:127]
	global_load_lds_dwordx4 v176, s[54:55]
	v_mfma_f32_32x32x16_bf16 v[96:111], v[128:131], v[148:151], v[96:111]
	v_mfma_f32_32x32x16_bf16 v[80:95], v[136:139], v[144:147], v[80:95]
	s_add_i32 m0, s56, 0x1000
	s_add_u32 s98, s54, 0x1000
	s_addc_u32 s99, s55, 0
	v_mfma_f32_32x32x16_bf16 v[64:79], v[128:131], v[144:147], v[64:79]
	global_load_lds_dwordx4 v176, s[98:99]
	v_mfma_f32_32x32x16_bf16 v[48:63], v[136:139], v[140:143], v[48:63]
	s_add_i32 m0, s56, 0x2000
	s_add_u32 s100, s54, 0x2000
	s_addc_u32 s101, s55, 0
	v_mfma_f32_32x32x16_bf16 v[32:47], v[128:131], v[140:143], v[32:47]
	global_load_lds_dwordx4 v176, s[100:101]
	v_mfma_f32_32x32x16_bf16 v[16:31], v[136:139], v[132:135], v[16:31]
	v_mfma_f32_32x32x16_bf16 v[0:15], v[128:131], v[132:135], v[0:15]
	v_add_u32_e32 v128, v183, v182
	ds_read_b128 v[148:151], v128
	ds_read_b128 v[144:147], v128 offset:2048
	ds_read_b128 v[140:143], v128 offset:4096
	ds_read_b128 v[132:135], v128 offset:6144
	v_add_u32_e32 v128, v184, v182
	ds_read_b128 v[136:139], v128 offset:16384
	ds_read_b128 v[128:131], v128 offset:18432
	s_waitcnt lgkmcnt(6)
	s_add_i32 m0, s56, 0x3000
	s_add_u32 s98, s54, 0x3000
	s_addc_u32 s99, s55, 0
	v_mfma_f32_32x32x16_bf16 v[112:127], v[164:167], v[172:175], v[112:127]
	global_load_lds_dwordx4 v176, s[98:99]
	v_mfma_f32_32x32x16_bf16 v[96:111], v[160:163], v[172:175], v[96:111]
	v_mfma_f32_32x32x16_bf16 v[80:95], v[164:167], v[168:171], v[80:95]
	s_add_i32 m0, s56, 0x4000
	v_mfma_f32_32x32x16_bf16 v[64:79], v[160:163], v[168:171], v[64:79]
	global_load_lds_dwordx4 v176, s[50:51]
	v_mfma_f32_32x32x16_bf16 v[48:63], v[164:167], v[156:159], v[48:63]
	s_add_i32 m0, s56, 0x5000
	s_add_u32 s98, s50, 0x1000
	s_addc_u32 s99, s51, 0
	v_mfma_f32_32x32x16_bf16 v[32:47], v[160:163], v[156:159], v[32:47]
	global_load_lds_dwordx4 v176, s[98:99]
	v_mfma_f32_32x32x16_bf16 v[16:31], v[164:167], v[152:155], v[16:31]
	v_mfma_f32_32x32x16_bf16 v[0:15], v[160:163], v[152:155], v[0:15]
	s_add_u32 s54, s54, 0x80000
	s_addc_u32 s55, s55, 0
	s_add_u32 s50, s50, 0x20000
	s_addc_u32 s51, s51, 0
	s_add_i32 s56, s75, 0x6000
	s_cmpk_lg_u32 s75, 0xc000
	s_cselect_b32 s75, s56, 0
	s_add_i32 s56, s76, 0x6000
	s_cmpk_lg_u32 s76, 0xc000
	s_cselect_b32 s76, s56, 0
	s_add_i32 s74, s74, 1
	s_waitcnt vmcnt(6) lgkmcnt(0)
	s_barrier
	s_cmp_lg_u32 s74, 62
	s_cbranch_scc1 .Lgemm_g6_main
